# FFT stage-1 epilogue: write-through stores issued behind the next group's twiddle loads (counted vmcnt waits no longer retire the slow sc1 stores first)
# speedup vs baseline: 1.0011x; 1.0011x over previous
; #define PG8_STAGE(bufoff, gbase, voff) do { _Pragma("unroll") for (int _i = 0; _i < 2; ++_i) \
;         __builtin_amdgcn_global_load_lds((const unsigned*)((const char*)(gbase) + (voff)[_i]), (LAS unsigned*)(lds + (bufoff) + ldsw + _i * 8192), 16, 0, 0); } while (0)
; #define PG8_STAGEB(bufoff, gbase, perm) do { _Pragma("unroll") for (int _i = 0; _i < 2; ++_i) \
;         __builtin_amdgcn_global_load_lds((const unsigned*)((const char*)(gbase) + ((BSEL && (perm)) ? voffBp[_i] : voffB[_i])), (LAS unsigned*)(lds + (bufoff) + ldsw + _i * 8192), 16, 0, 0); } while (0)
; #define PG8_WAIT_V(n) asm volatile("s_waitcnt vmcnt(" #n ")" ::: "memory")
; #define PG8_WAIT_L(n) asm volatile("s_waitcnt lgkmcnt(" #n ")" ::: "memory")
; #define PG8_BAR __builtin_amdgcn_s_barrier()
; template <class Epi, bool BSEL = false>
; __device__ __forceinline__ void gemm_phase(LAS unsigned char* lds, const Gemm g, const Order& S, const Epi& E, const int tid) {
;     ...
;         for (int t = 0; t < nt; t += 2) {
;             const bool last = (t == nt - 2);
;             const char* a1 = cA + (size_t)(t + 1) * kstep;
;             const char* a2 = last ? nA : cA + (size_t)(t + 2) * kstep; const char* b2 = last ? nB : cB + (size_t)(t + 2) * kstep;
;             const char* a3 = a2 + kstep; const char* b3 = b2 + kstep;
;             const bool p2 = last ? nP : cP; const size_t h2 = last ? nhB : chB;
;             PG8_LDB(B0, 0, 0); PG8_LDB(B1, 0, 1); PG8_SCHED; PG8_LDA(At, 0, 0); PG8_STAGE(PG8_SA(1, 1), a1 + hstepA, voffA);
;             PG8_WAIT_V(8); PG8_WAIT_L(0); PG8_BAR; PG8_MMA(0, 0, At, B0); PG8_MMA(0, 1, At, B1); PG8_BAR; PG8_SCHED;
;             PG8_LDA(At, 0, 1); PG8_STAGEB(PG8_SB(0, 0), b2, p2); PG8_STAGEB(PG8_SB(0, 1), b2 + h2, p2); PG8_STAGE(PG8_SA(0, 0), a2, voffA);
;             PG8_WAIT_V(8); PG8_WAIT_L(0); PG8_BAR; PG8_MMA(1, 0, At, B0); PG8_MMA(1, 1, At, B1); PG8_BAR; PG8_SCHED;
;             PG8_LDB(B0, 1, 0); PG8_LDB(B1, 1, 1); PG8_SCHED; PG8_LDA(At, 1, 0); PG8_STAGE(PG8_SA(0, 1), a2 + hstepA, voffA);
;             PG8_WAIT_V(8); PG8_WAIT_L(0); PG8_BAR; PG8_MMA(0, 0, At, B0); PG8_MMA(0, 1, At, B1); PG8_BAR; PG8_SCHED;
;             PG8_LDA(At, 1, 1); PG8_STAGEB(PG8_SB(1, 0), b3, p2); PG8_STAGEB(PG8_SB(1, 1), b3 + h2, p2); PG8_STAGE(PG8_SA(1, 0), a3, voffA);
;             PG8_WAIT_V(8); PG8_WAIT_L(0); PG8_BAR; PG8_MMA(1, 0, At, B0); PG8_MMA(1, 1, At, B1); PG8_BAR; PG8_SCHED;
.LBB0_826:
	s_xor_b64 s[38:39], s[40:41], -1
	v_add_u32_e32 v145, s53, v139
	s_and_b64 s[2:3], s[40:41], exec
	ds_read_b128 v[146:149], v145
	ds_read_b128 v[150:153], v145 offset:1024
	ds_read_b128 v[154:157], v145 offset:2048
	ds_read_b128 v[158:161], v145 offset:3072
	v_add_u32_e32 v145, s54, v139
	s_cselect_b32 s45, s1, s1
	s_cselect_b32 s44, s0, s0
	s_add_u32 s58, s0, 0x8080
	ds_read_b128 v[162:165], v145
	ds_read_b128 v[166:169], v145 offset:1024
	ds_read_b128 v[170:173], v145 offset:2048
	ds_read_b128 v[174:177], v145 offset:3072
	s_addc_u32 s59, s1, 0
	s_add_u32 s42, s44, 0x8000
	s_addc_u32 s43, s45, 0
	s_and_b64 s[2:3], s[40:41], exec
	s_cselect_b32 s2, s36, s4
	s_cselect_b32 s3, s37, s5
	s_add_u32 s60, s2, 0x8000
	s_addc_u32 s61, s3, 0
	v_lshl_add_u64 v[198:199], s[58:59], 0, v[128:129]
	s_add_i32 m0, s20, 0xc000
	ds_read_b128 v[178:181], v144
	ds_read_b128 v[182:185], v144 offset:1024
	ds_read_b128 v[186:189], v144 offset:2048
	ds_read_b128 v[190:193], v144 offset:3072
	ds_read_b128 v[194:197], v144 offset:4096
	ds_read_b128 v[202:205], v144 offset:5120
	ds_read_b128 v[206:209], v144 offset:6144
	ds_read_b128 v[210:213], v144 offset:7168
	global_load_lds_dwordx4 v[198:199], off
	v_lshl_add_u64 v[198:199], s[58:59], 0, v[132:133]
	s_add_i32 m0, s20, 0xe000
	s_nop 0
	global_load_lds_dwordx4 v[198:199], off
	s_waitcnt vmcnt(8)
	s_waitcnt lgkmcnt(0)
	s_barrier
	s_setprio 1
	s_waitcnt lgkmcnt(0)
	v_mfma_f32_16x16x32_bf16 v[124:127], v[146:149], v[178:181], v[124:127]
	v_mfma_f32_16x16x32_bf16 v[120:123], v[154:157], v[178:181], v[120:123]
	v_mfma_f32_16x16x32_bf16 v[116:119], v[146:149], v[186:189], v[116:119]
	v_mfma_f32_16x16x32_bf16 v[112:115], v[154:157], v[186:189], v[112:115]
	v_mfma_f32_16x16x32_bf16 v[108:111], v[146:149], v[194:197], v[108:111]
	v_mfma_f32_16x16x32_bf16 v[104:107], v[154:157], v[194:197], v[104:107]
	v_mfma_f32_16x16x32_bf16 v[100:103], v[146:149], v[206:209], v[100:103]
	v_mfma_f32_16x16x32_bf16 v[96:99], v[154:157], v[206:209], v[96:99]
	v_mfma_f32_16x16x32_bf16 v[124:127], v[150:153], v[182:185], v[124:127]
	v_mfma_f32_16x16x32_bf16 v[120:123], v[158:161], v[182:185], v[120:123]
	v_mfma_f32_16x16x32_bf16 v[116:119], v[150:153], v[190:193], v[116:119]
	v_mfma_f32_16x16x32_bf16 v[112:115], v[158:161], v[190:193], v[112:115]
	v_mfma_f32_16x16x32_bf16 v[108:111], v[150:153], v[202:205], v[108:111]
	v_mfma_f32_16x16x32_bf16 v[104:107], v[158:161], v[202:205], v[104:107]
	v_mfma_f32_16x16x32_bf16 v[100:103], v[150:153], v[210:213], v[100:103]
	v_mfma_f32_16x16x32_bf16 v[96:99], v[158:161], v[210:213], v[96:99]
	s_setprio 0
	s_setprio 1
	v_mfma_f32_16x16x32_bf16 v[92:95], v[162:165], v[178:181], v[92:95]
	v_mfma_f32_16x16x32_bf16 v[88:91], v[170:173], v[178:181], v[88:91]
	v_mfma_f32_16x16x32_bf16 v[84:87], v[162:165], v[186:189], v[84:87]
	v_mfma_f32_16x16x32_bf16 v[80:83], v[170:173], v[186:189], v[80:83]
	v_mfma_f32_16x16x32_bf16 v[76:79], v[162:165], v[194:197], v[76:79]
	v_mfma_f32_16x16x32_bf16 v[72:75], v[170:173], v[194:197], v[72:75]
	v_mfma_f32_16x16x32_bf16 v[68:71], v[162:165], v[206:209], v[68:71]
	v_mfma_f32_16x16x32_bf16 v[64:67], v[170:173], v[206:209], v[64:67]
	v_mfma_f32_16x16x32_bf16 v[92:95], v[166:169], v[182:185], v[92:95]
	v_mfma_f32_16x16x32_bf16 v[88:91], v[174:177], v[182:185], v[88:91]
	v_mfma_f32_16x16x32_bf16 v[84:87], v[166:169], v[190:193], v[84:87]
	v_mfma_f32_16x16x32_bf16 v[80:83], v[174:177], v[190:193], v[80:83]
	v_mfma_f32_16x16x32_bf16 v[76:79], v[166:169], v[202:205], v[76:79]
	v_mfma_f32_16x16x32_bf16 v[72:75], v[174:177], v[202:205], v[72:75]
	v_mfma_f32_16x16x32_bf16 v[68:71], v[166:169], v[210:213], v[68:71]
	v_mfma_f32_16x16x32_bf16 v[64:67], v[174:177], v[210:213], v[64:67]
	s_setprio 0
	s_barrier
	s_add_i32 s35, s53, s15
	v_lshl_add_u64 v[198:199], s[2:3], 0, v[130:131]
	s_mov_b32 m0, s35
	ds_read_b128 v[178:181], v144 offset:16384
	ds_read_b128 v[182:185], v144 offset:17408
	ds_read_b128 v[186:189], v144 offset:18432
	ds_read_b128 v[190:193], v144 offset:19456
	ds_read_b128 v[194:197], v144 offset:20480
	ds_read_b128 v[202:205], v144 offset:21504
	ds_read_b128 v[206:209], v144 offset:22528
	ds_read_b128 v[210:213], v144 offset:23552
	global_load_lds_dwordx4 v[198:199], off
	v_lshl_add_u64 v[214:215], s[2:3], 0, v[134:135]
	s_add_i32 m0, s35, 0x2000
	s_add_i32 s35, s54, s15
	global_load_lds_dwordx4 v[214:215], off
	v_lshl_add_u64 v[216:217], s[60:61], 0, v[130:131]
	s_mov_b32 m0, s35
	v_lshl_add_u64 v[218:219], s[44:45], 0, v[132:133]
	global_load_lds_dwordx4 v[216:217], off
	v_lshl_add_u64 v[216:217], s[60:61], 0, v[134:135]
	s_add_i32 m0, s35, 0x2000
	s_nop 0
	global_load_lds_dwordx4 v[216:217], off
	v_lshl_add_u64 v[216:217], s[44:45], 0, v[128:129]
	s_mov_b32 m0, s20
	s_nop 0
	global_load_lds_dwordx4 v[216:217], off
	s_mov_b32 m0, s21
	s_nop 0
	global_load_lds_dwordx4 v[218:219], off
	s_waitcnt vmcnt(8)
	s_waitcnt lgkmcnt(0)
	s_barrier
; #define PG8_STAGE(bufoff, gbase, voff) do { _Pragma("unroll") for (int _i = 0; _i < 2; ++_i) \
;         __builtin_amdgcn_global_load_lds((const unsigned*)((const char*)(gbase) + (voff)[_i]), (LAS unsigned*)(lds + (bufoff) + ldsw + _i * 8192), 16, 0, 0); } while (0)
; #define PG8_STAGEB(bufoff, gbase, perm) do { _Pragma("unroll") for (int _i = 0; _i < 2; ++_i) \
;         __builtin_amdgcn_global_load_lds((const unsigned*)((const char*)(gbase) + ((BSEL && (perm)) ? voffBp[_i] : voffB[_i])), (LAS unsigned*)(lds + (bufoff) + ldsw + _i * 8192), 16, 0, 0); } while (0)
; #define PG8_LDA(dst, b, h) do { _Pragma("unroll") for (int m = 0; m < 4; ++m) _Pragma("unroll") for (int k = 0; k < 2; ++k) dst[m][k] = *(const LAS bf16x8*)(lds + PG8_SA(b, h) + aoff + m * 2048 + k * 1024); } while (0)
; #define PG8_LDB(dst, b, h) do { _Pragma("unroll") for (int n = 0; n < 2; ++n) _Pragma("unroll") for (int k = 0; k < 2; ++k) dst[n][k] = *(const LAS bf16x8*)(lds + PG8_SB(b, h) + boff + n * 2048 + k * 1024); } while (0)
; #define PG8_WAIT_V(n) asm volatile("s_waitcnt vmcnt(" #n ")" ::: "memory")
; #define PG8_WAIT_L(n) asm volatile("s_waitcnt lgkmcnt(" #n ")" ::: "memory")
; template <class Epi, bool BSEL = false>
; __device__ __forceinline__ void gemm_phase(LAS unsigned char* lds, const Gemm g, const Order& S, const Epi& E, const int tid) {
;     ...
;             PG8_LDB(B0, 0, 0); PG8_LDB(B1, 0, 1); PG8_SCHED; PG8_LDA(At, 0, 0); PG8_STAGE(PG8_SA(1, 1), a1 + hstepA, voffA);
;             PG8_WAIT_V(8); PG8_WAIT_L(0); PG8_BAR; PG8_MMA(0, 0, At, B0); PG8_MMA(0, 1, At, B1); PG8_BAR; PG8_SCHED;
;             PG8_LDA(At, 0, 1); PG8_STAGEB(PG8_SB(0, 0), b2, p2); PG8_STAGEB(PG8_SB(0, 1), b2 + h2, p2); PG8_STAGE(PG8_SA(0, 0), a2, voffA);
;             PG8_WAIT_V(8); PG8_WAIT_L(0); PG8_BAR; PG8_MMA(1, 0, At, B0); PG8_MMA(1, 1, At, B1); PG8_BAR; PG8_SCHED;
;             PG8_LDB(B0, 1, 0); PG8_LDB(B1, 1, 1); PG8_SCHED; PG8_LDA(At, 1, 0); PG8_STAGE(PG8_SA(0, 1), a2 + hstepA, voffA);
;             PG8_WAIT_V(8); PG8_WAIT_L(0); PG8_BAR; PG8_MMA(0, 0, At, B0); PG8_MMA(0, 1, At, B1); PG8_BAR; PG8_SCHED;
;             PG8_LDA(At, 1, 1); PG8_STAGEB(PG8_SB(1, 0), b3, p2); PG8_STAGEB(PG8_SB(1, 1), b3 + h2, p2); PG8_STAGE(PG8_SA(1, 0), a3, voffA);
;             PG8_WAIT_V(8); PG8_WAIT_L(0); PG8_BAR; PG8_MMA(1, 0, At, B0); PG8_MMA(1, 1, At, B1); PG8_BAR; PG8_SCHED;
	s_setprio 1
	s_waitcnt lgkmcnt(0)
	v_mfma_f32_16x16x32_bf16 v[60:63], v[146:149], v[178:181], v[60:63]
	v_mfma_f32_16x16x32_bf16 v[56:59], v[154:157], v[178:181], v[56:59]
	v_mfma_f32_16x16x32_bf16 v[52:55], v[146:149], v[186:189], v[52:55]
	v_mfma_f32_16x16x32_bf16 v[48:51], v[154:157], v[186:189], v[48:51]
	v_mfma_f32_16x16x32_bf16 v[44:47], v[146:149], v[194:197], v[44:47]
	v_mfma_f32_16x16x32_bf16 v[40:43], v[154:157], v[194:197], v[40:43]
	v_mfma_f32_16x16x32_bf16 v[36:39], v[146:149], v[206:209], v[36:39]
	v_mfma_f32_16x16x32_bf16 v[32:35], v[154:157], v[206:209], v[32:35]
	v_mfma_f32_16x16x32_bf16 v[60:63], v[150:153], v[182:185], v[60:63]
	v_mfma_f32_16x16x32_bf16 v[56:59], v[158:161], v[182:185], v[56:59]
	v_mfma_f32_16x16x32_bf16 v[52:55], v[150:153], v[190:193], v[52:55]
	v_mfma_f32_16x16x32_bf16 v[48:51], v[158:161], v[190:193], v[48:51]
	v_mfma_f32_16x16x32_bf16 v[44:47], v[150:153], v[202:205], v[44:47]
	v_mfma_f32_16x16x32_bf16 v[40:43], v[158:161], v[202:205], v[40:43]
	v_mfma_f32_16x16x32_bf16 v[36:39], v[150:153], v[210:213], v[36:39]
	v_mfma_f32_16x16x32_bf16 v[32:35], v[158:161], v[210:213], v[32:35]
	s_setprio 0
	s_setprio 1
	v_mfma_f32_16x16x32_bf16 v[28:31], v[162:165], v[178:181], v[28:31]
	v_mfma_f32_16x16x32_bf16 v[24:27], v[170:173], v[178:181], v[24:27]
	v_mfma_f32_16x16x32_bf16 v[20:23], v[162:165], v[186:189], v[20:23]
	v_mfma_f32_16x16x32_bf16 v[16:19], v[170:173], v[186:189], v[16:19]
	v_mfma_f32_16x16x32_bf16 v[12:15], v[162:165], v[194:197], v[12:15]
	v_mfma_f32_16x16x32_bf16 v[8:11], v[170:173], v[194:197], v[8:11]
	v_mfma_f32_16x16x32_bf16 v[4:7], v[162:165], v[206:209], v[4:7]
	v_mfma_f32_16x16x32_bf16 v[0:3], v[170:173], v[206:209], v[0:3]
	v_mfma_f32_16x16x32_bf16 v[28:31], v[166:169], v[182:185], v[28:31]
	v_mfma_f32_16x16x32_bf16 v[24:27], v[174:177], v[182:185], v[24:27]
	v_mfma_f32_16x16x32_bf16 v[20:23], v[166:169], v[190:193], v[20:23]
	v_mfma_f32_16x16x32_bf16 v[16:19], v[174:177], v[190:193], v[16:19]
	v_mfma_f32_16x16x32_bf16 v[12:15], v[166:169], v[202:205], v[12:15]
	v_mfma_f32_16x16x32_bf16 v[8:11], v[174:177], v[202:205], v[8:11]
	v_mfma_f32_16x16x32_bf16 v[4:7], v[166:169], v[210:213], v[4:7]
	v_mfma_f32_16x16x32_bf16 v[0:3], v[174:177], v[210:213], v[0:3]
	s_setprio 0
	s_barrier
	s_add_i32 s35, 0, 0x18000
	v_add_u32_e32 v145, s35, v139
	s_add_i32 s44, 0, 0x1c000
	ds_read_b128 v[146:149], v145
	ds_read_b128 v[150:153], v145 offset:1024
	ds_read_b128 v[154:157], v145 offset:2048
	ds_read_b128 v[158:161], v145 offset:3072
	v_add_u32_e32 v145, s44, v139
	ds_read_b128 v[162:165], v145
	ds_read_b128 v[166:169], v145 offset:1024
	ds_read_b128 v[170:173], v145 offset:2048
	ds_read_b128 v[174:177], v145 offset:3072
	s_mov_b32 m0, s46
	v_lshl_add_u64 v[220:221], s[42:43], 0, v[128:129]
	ds_read_b128 v[178:181], v144 offset:32768
	ds_read_b128 v[182:185], v144 offset:33792
	ds_read_b128 v[186:189], v144 offset:34816
	ds_read_b128 v[190:193], v144 offset:35840
	ds_read_b128 v[194:197], v144 offset:36864
	ds_read_b128 v[202:205], v144 offset:37888
	ds_read_b128 v[206:209], v144 offset:38912
	ds_read_b128 v[210:213], v144 offset:39936
	global_load_lds_dwordx4 v[220:221], off
	v_lshl_add_u64 v[220:221], s[42:43], 0, v[132:133]
	s_mov_b32 m0, s47
	s_nop 0
	global_load_lds_dwordx4 v[220:221], off
	s_waitcnt vmcnt(8)
	s_waitcnt lgkmcnt(0)
	s_barrier
	s_setprio 1
	s_waitcnt lgkmcnt(0)
	v_mfma_f32_16x16x32_bf16 v[124:127], v[146:149], v[178:181], v[124:127]
	v_mfma_f32_16x16x32_bf16 v[120:123], v[154:157], v[178:181], v[120:123]
	v_mfma_f32_16x16x32_bf16 v[116:119], v[146:149], v[186:189], v[116:119]
	v_mfma_f32_16x16x32_bf16 v[112:115], v[154:157], v[186:189], v[112:115]
	v_mfma_f32_16x16x32_bf16 v[108:111], v[146:149], v[194:197], v[108:111]
	v_mfma_f32_16x16x32_bf16 v[104:107], v[154:157], v[194:197], v[104:107]
	v_mfma_f32_16x16x32_bf16 v[100:103], v[146:149], v[206:209], v[100:103]
	v_mfma_f32_16x16x32_bf16 v[96:99], v[154:157], v[206:209], v[96:99]
	v_mfma_f32_16x16x32_bf16 v[124:127], v[150:153], v[182:185], v[124:127]
	v_mfma_f32_16x16x32_bf16 v[120:123], v[158:161], v[182:185], v[120:123]
	v_mfma_f32_16x16x32_bf16 v[116:119], v[150:153], v[190:193], v[116:119]
	v_mfma_f32_16x16x32_bf16 v[112:115], v[158:161], v[190:193], v[112:115]
	v_mfma_f32_16x16x32_bf16 v[108:111], v[150:153], v[202:205], v[108:111]
	v_mfma_f32_16x16x32_bf16 v[104:107], v[158:161], v[202:205], v[104:107]
	v_mfma_f32_16x16x32_bf16 v[100:103], v[150:153], v[210:213], v[100:103]
	v_mfma_f32_16x16x32_bf16 v[96:99], v[158:161], v[210:213], v[96:99]
	s_setprio 0
	s_setprio 1
	v_mfma_f32_16x16x32_bf16 v[92:95], v[162:165], v[178:181], v[92:95]
	v_mfma_f32_16x16x32_bf16 v[88:91], v[170:173], v[178:181], v[88:91]
	v_mfma_f32_16x16x32_bf16 v[84:87], v[162:165], v[186:189], v[84:87]
	v_mfma_f32_16x16x32_bf16 v[80:83], v[170:173], v[186:189], v[80:83]
	v_mfma_f32_16x16x32_bf16 v[76:79], v[162:165], v[194:197], v[76:79]
	v_mfma_f32_16x16x32_bf16 v[72:75], v[170:173], v[194:197], v[72:75]
	v_mfma_f32_16x16x32_bf16 v[68:71], v[162:165], v[206:209], v[68:71]
	v_mfma_f32_16x16x32_bf16 v[64:67], v[170:173], v[206:209], v[64:67]
	v_mfma_f32_16x16x32_bf16 v[92:95], v[166:169], v[182:185], v[92:95]
	v_mfma_f32_16x16x32_bf16 v[88:91], v[174:177], v[182:185], v[88:91]
	v_mfma_f32_16x16x32_bf16 v[84:87], v[166:169], v[190:193], v[84:87]
	v_mfma_f32_16x16x32_bf16 v[80:83], v[174:177], v[190:193], v[80:83]
	v_mfma_f32_16x16x32_bf16 v[76:79], v[166:169], v[202:205], v[76:79]
	v_mfma_f32_16x16x32_bf16 v[72:75], v[174:177], v[202:205], v[72:75]
	v_mfma_f32_16x16x32_bf16 v[68:71], v[166:169], v[210:213], v[68:71]
	v_mfma_f32_16x16x32_bf16 v[64:67], v[174:177], v[210:213], v[64:67]
	s_setprio 0
	s_barrier
; #define PG8_STAGE(bufoff, gbase, voff) do { _Pragma("unroll") for (int _i = 0; _i < 2; ++_i) \
;         __builtin_amdgcn_global_load_lds((const unsigned*)((const char*)(gbase) + (voff)[_i]), (LAS unsigned*)(lds + (bufoff) + ldsw + _i * 8192), 16, 0, 0); } while (0)
; #define PG8_STAGEB(bufoff, gbase, perm) do { _Pragma("unroll") for (int _i = 0; _i < 2; ++_i) \
;         __builtin_amdgcn_global_load_lds((const unsigned*)((const char*)(gbase) + ((BSEL && (perm)) ? voffBp[_i] : voffB[_i])), (LAS unsigned*)(lds + (bufoff) + ldsw + _i * 8192), 16, 0, 0); } while (0)
; #define PG8_LDA(dst, b, h) do { _Pragma("unroll") for (int m = 0; m < 4; ++m) _Pragma("unroll") for (int k = 0; k < 2; ++k) dst[m][k] = *(const LAS bf16x8*)(lds + PG8_SA(b, h) + aoff + m * 2048 + k * 1024); } while (0)
; template <class Epi, bool BSEL = false>
; __device__ __forceinline__ void gemm_phase(LAS unsigned char* lds, const Gemm g, const Order& S, const Epi& E, const int tid) {
;     ...
;             PG8_LDA(At, 1, 1); PG8_STAGEB(PG8_SB(1, 0), b3, p2); PG8_STAGEB(PG8_SB(1, 1), b3 + h2, p2); PG8_STAGE(PG8_SA(1, 0), a3, voffA);
;             PG8_WAIT_V(8); PG8_WAIT_L(0); PG8_BAR; PG8_MMA(1, 0, At, B0); PG8_MMA(1, 1, At, B1); PG8_BAR; PG8_SCHED;
;         }
;         if constexpr (ALIGN_EPI) { if (wr == 0) PG8_BAR; }
;     __device__ __forceinline__ void operator()(const f32x4 (&acc)[2][2][4][2], const Unit& u, int wr, int wc, int fr, int fq) const {
;         if (wr != 0) return;
;         const __amdgpu_buffer_rsrc_t rsrc = __builtin_amdgcn_make_buffer_rsrc(YT, 0, 65536 * 128 * 2, 0x00020000);
; #pragma unroll
;         for (int m = 0; m < 4; ++m) { const int k1 = 16 * m + fr;
; #pragma unroll
;             for (int bj = 0; bj < 2; ++bj) { const int col = 4 * u.pn + 2 * bj + (wc >> 1), b = col >> 8, ch = col & 255;
;                 const int n2 = 32 * (wc & 1) + 8 * fq;
;                 const unsigned rowo = (unsigned)((((size_t)(b * 64 + k1) * 256 + ch) * 128 + n2) * 2);
;                 int kk = k1; asm volatile("" : "+v"(kk));
;                 f32x4 pr[2], pi[2];
; #pragma unroll
;                 for (int n = 0; n < 2; ++n) { const f32x4 yr = acc[0][bj][m][n], yi = acc[1][bj][m][n];
; #pragma unroll
;                     for (int i = 0; i < 4; ++i) { const f32x2 cs = TW[(n2 + 4 * n + i) * kk]; pr[n][i] = yr[i] * cs.x + yi[i] * cs.y; pi[n][i] = yi[i] * cs.x - yr[i] * cs.y; } }
	s_add_i32 s35, s35, s15
	v_lshl_add_u64 v[198:199], v[198:199], 0, s[28:29]
	s_mov_b32 m0, s35
	ds_read_b128 v[178:181], v144 offset:49152
	ds_read_b128 v[182:185], v144 offset:50176
	ds_read_b128 v[186:189], v144 offset:51200
	ds_read_b128 v[190:193], v144 offset:52224
	ds_read_b128 v[194:197], v144 offset:53248
	ds_read_b128 v[202:205], v144 offset:54272
	ds_read_b128 v[206:209], v144 offset:55296
	ds_read_b128 v[210:213], v144 offset:56320
	global_load_lds_dwordx4 v[198:199], off
	s_add_i32 m0, s35, 0x2000
	s_add_u32 s2, s2, 0x8080
	v_lshl_add_u64 v[198:199], v[214:215], 0, s[28:29]
	s_addc_u32 s3, s3, 0
	s_add_i32 s35, s44, s15
	global_load_lds_dwordx4 v[198:199], off
	v_lshl_add_u64 v[198:199], s[2:3], 0, v[130:131]
	s_mov_b32 m0, s35
	s_nop 0
	global_load_lds_dwordx4 v[198:199], off
	v_lshl_add_u64 v[198:199], s[2:3], 0, v[134:135]
	s_add_i32 m0, s35, 0x2000
	s_nop 0
	global_load_lds_dwordx4 v[198:199], off
	v_lshl_add_u64 v[198:199], v[216:217], 0, s[28:29]
	s_mov_b32 m0, s49
	s_nop 0
	global_load_lds_dwordx4 v[198:199], off
	v_lshl_add_u64 v[198:199], v[218:219], 0, s[28:29]
	s_mov_b32 m0, s51
	s_nop 0
	global_load_lds_dwordx4 v[198:199], off
	s_waitcnt vmcnt(8)
	s_waitcnt lgkmcnt(0)
	s_barrier
	s_setprio 1
	s_waitcnt lgkmcnt(0)
	v_mfma_f32_16x16x32_bf16 v[60:63], v[146:149], v[178:181], v[60:63]
	v_mfma_f32_16x16x32_bf16 v[56:59], v[154:157], v[178:181], v[56:59]
	v_mfma_f32_16x16x32_bf16 v[52:55], v[146:149], v[186:189], v[52:55]
	v_mfma_f32_16x16x32_bf16 v[48:51], v[154:157], v[186:189], v[48:51]
	v_mfma_f32_16x16x32_bf16 v[44:47], v[146:149], v[194:197], v[44:47]
	v_mfma_f32_16x16x32_bf16 v[40:43], v[154:157], v[194:197], v[40:43]
	v_mfma_f32_16x16x32_bf16 v[36:39], v[146:149], v[206:209], v[36:39]
	v_mfma_f32_16x16x32_bf16 v[32:35], v[154:157], v[206:209], v[32:35]
	v_mfma_f32_16x16x32_bf16 v[60:63], v[150:153], v[182:185], v[60:63]
	v_mfma_f32_16x16x32_bf16 v[56:59], v[158:161], v[182:185], v[56:59]
	v_mfma_f32_16x16x32_bf16 v[52:55], v[150:153], v[190:193], v[52:55]
	v_mfma_f32_16x16x32_bf16 v[48:51], v[158:161], v[190:193], v[48:51]
	v_mfma_f32_16x16x32_bf16 v[44:47], v[150:153], v[202:205], v[44:47]
	v_mfma_f32_16x16x32_bf16 v[40:43], v[158:161], v[202:205], v[40:43]
	v_mfma_f32_16x16x32_bf16 v[36:39], v[150:153], v[210:213], v[36:39]
	v_mfma_f32_16x16x32_bf16 v[32:35], v[158:161], v[210:213], v[32:35]
	s_setprio 0
	s_setprio 1
	v_mfma_f32_16x16x32_bf16 v[28:31], v[162:165], v[178:181], v[28:31]
	v_mfma_f32_16x16x32_bf16 v[24:27], v[170:173], v[178:181], v[24:27]
	v_mfma_f32_16x16x32_bf16 v[20:23], v[162:165], v[186:189], v[20:23]
	v_mfma_f32_16x16x32_bf16 v[16:19], v[170:173], v[186:189], v[16:19]
	v_mfma_f32_16x16x32_bf16 v[12:15], v[162:165], v[194:197], v[12:15]
	v_mfma_f32_16x16x32_bf16 v[8:11], v[170:173], v[194:197], v[8:11]
	v_mfma_f32_16x16x32_bf16 v[4:7], v[162:165], v[206:209], v[4:7]
	v_mfma_f32_16x16x32_bf16 v[0:3], v[170:173], v[206:209], v[0:3]
	v_mfma_f32_16x16x32_bf16 v[28:31], v[166:169], v[182:185], v[28:31]
	v_mfma_f32_16x16x32_bf16 v[24:27], v[174:177], v[182:185], v[24:27]
	v_mfma_f32_16x16x32_bf16 v[20:23], v[166:169], v[190:193], v[20:23]
	v_mfma_f32_16x16x32_bf16 v[16:19], v[174:177], v[190:193], v[16:19]
	v_mfma_f32_16x16x32_bf16 v[12:15], v[166:169], v[202:205], v[12:15]
	v_mfma_f32_16x16x32_bf16 v[8:11], v[174:177], v[202:205], v[8:11]
	v_mfma_f32_16x16x32_bf16 v[4:7], v[166:169], v[210:213], v[4:7]
	v_mfma_f32_16x16x32_bf16 v[0:3], v[174:177], v[210:213], v[0:3]
	s_setprio 0
	s_barrier
	s_andn2_b64 vcc, exec, s[30:31]
	s_cbranch_vccnz .LBB0_828
	v_mov_b32_e32 v145, v138
	s_barrier
	v_mov_b32_e32 v162, v124
	v_mul_lo_u32 v146, v145, v140
	v_ashrrev_i32_e32 v147, 31, v146
	v_lshl_add_u64 v[148:149], v[146:147], 3, s[26:27]
	v_add_u32_e32 v146, v146, v145
	v_ashrrev_i32_e32 v147, 31, v146
	v_lshl_add_u64 v[150:151], v[146:147], 3, s[26:27]
	v_add_u32_e32 v146, v146, v145
	v_ashrrev_i32_e32 v147, 31, v146
	v_lshl_add_u64 v[152:153], v[146:147], 3, s[26:27]
	v_add_u32_e32 v146, v146, v145
	v_ashrrev_i32_e32 v147, 31, v146
	v_lshl_add_u64 v[154:155], v[146:147], 3, s[26:27]
	v_add_u32_e32 v146, v146, v145
	global_load_dwordx2 v[148:149], v[148:149], off
	v_ashrrev_i32_e32 v147, 31, v146
	global_load_dwordx2 v[150:151], v[150:151], off
	v_lshl_add_u64 v[156:157], v[146:147], 3, s[26:27]
	v_add_u32_e32 v146, v146, v145
	global_load_dwordx2 v[152:153], v[152:153], off
	v_ashrrev_i32_e32 v147, 31, v146
	global_load_dwordx2 v[154:155], v[154:155], off
	v_lshl_add_u64 v[158:159], v[146:147], 3, s[26:27]
	v_add_u32_e32 v146, v146, v145
	global_load_dwordx2 v[156:157], v[156:157], off
	v_ashrrev_i32_e32 v147, 31, v146
	global_load_dwordx2 v[158:159], v[158:159], off
	v_lshl_add_u64 v[160:161], v[146:147], 3, s[26:27]
	global_load_dwordx2 v[160:161], v[160:161], off
	v_add_u32_e32 v146, v146, v145
	v_ashrrev_i32_e32 v147, 31, v146
	v_lshl_add_u64 v[146:147], v[146:147], 3, s[26:27]
	global_load_dwordx2 v[146:147], v[146:147], off
	v_mov_b32_e32 v163, v60
	v_mov_b32_e32 v164, v60
	v_mov_b32_e32 v165, v124
	v_mov_b32_e32 v166, v125
	v_mov_b32_e32 v167, v61
	v_mov_b32_e32 v168, v61
	v_mov_b32_e32 v169, v125
	v_mov_b32_e32 v170, v126
	v_mov_b32_e32 v171, v62
	v_mov_b32_e32 v172, v62
	v_mov_b32_e32 v173, v126
	v_mov_b32_e32 v174, v127
	v_mov_b32_e32 v175, v63
	v_mov_b32_e32 v176, v63
	v_mov_b32_e32 v177, v127
	v_mov_b32_e32 v178, v120
	v_mov_b32_e32 v179, v56
	v_mov_b32_e32 v180, v56
	v_mov_b32_e32 v181, v120
	v_mov_b32_e32 v182, v121
	v_mov_b32_e32 v183, v57
	v_mov_b32_e32 v184, v57
	v_mov_b32_e32 v185, v121
	v_mov_b32_e32 v186, v122
	v_mov_b32_e32 v187, v58
	s_lshl_b32 s3, s48, 2
	s_and_b32 s2, s48, 0xffc0
	s_and_b32 s3, s3, 0xfc
	v_or_b32_e32 v145, s2, v138
	s_or_b32 s3, s3, s52
	v_lshl_or_b32 v145, v145, 15, v140
	s_lshl_b32 s35, s3, 7
	v_or_b32_e32 v188, s35, v145
	s_or_b32 s3, s35, 0x100
	v_or_b32_e32 v145, s3, v145
	v_lshlrev_b32_e32 v145, 1, v145
	s_waitcnt vmcnt(0)
; __device__ __forceinline__ unsigned cvt_pk_bf16(float lo, float hi) { unsigned r; asm volatile("v_cvt_pk_bf16_f32 %0, %1, %2" : "=v"(r) : "v"(lo), "v"(hi)); return r; }
;     __device__ __forceinline__ void operator()(const f32x4 (&acc)[2][2][4][2], const Unit& u, int wr, int wc, int fr, int fq) const {
;     ...
;         for (int m = 0; m < 4; ++m) { const int k1 = 16 * m + fr;
; #pragma unroll
;             for (int bj = 0; bj < 2; ++bj) { const int col = 4 * u.pn + 2 * bj + (wc >> 1), b = col >> 8, ch = col & 255;
;                 const int n2 = 32 * (wc & 1) + 8 * fq;
;                 const unsigned rowo = (unsigned)((((size_t)(b * 64 + k1) * 256 + ch) * 128 + n2) * 2);
;                 int kk = k1; asm volatile("" : "+v"(kk));
;                 f32x4 pr[2], pi[2];
; #pragma unroll
;                 for (int n = 0; n < 2; ++n) { const f32x4 yr = acc[0][bj][m][n], yi = acc[1][bj][m][n];
; #pragma unroll
;                     for (int i = 0; i < 4; ++i) { const f32x2 cs = TW[(n2 + 4 * n + i) * kk]; pr[n][i] = yr[i] * cs.x + yi[i] * cs.y; pi[n][i] = yi[i] * cs.x - yr[i] * cs.y; } }
;                 u32x4 w; w.x = cvt_pk_bf16(pr[0][0], pr[0][1]); w.y = cvt_pk_bf16(pr[0][2], pr[0][3]); w.z = cvt_pk_bf16(pr[1][0], pr[1][1]); w.w = cvt_pk_bf16(pr[1][2], pr[1][3]);
;                 __builtin_amdgcn_raw_buffer_store_b128(w, rsrc, rowo, 0, 16);
;                 w.x = cvt_pk_bf16(pi[0][0], pi[0][1]); w.y = cvt_pk_bf16(pi[0][2], pi[0][3]); w.z = cvt_pk_bf16(pi[1][0], pi[1][1]); w.w = cvt_pk_bf16(pi[1][2], pi[1][3]);
;                 __builtin_amdgcn_raw_buffer_store_b128(w, rsrc, rowo + 128, 0, 16);
	v_pk_mul_f32 v[162:163], v[162:163], v[148:149]
	v_pk_mul_f32 v[148:149], v[164:165], v[148:149]
	v_add_f32_e32 v162, v162, v163
	v_sub_f32_e32 v163, v148, v149
	v_pk_mul_f32 v[148:149], v[166:167], v[150:151]
	v_pk_mul_f32 v[150:151], v[168:169], v[150:151]
	v_add_f32_e32 v164, v148, v149
	v_pk_mul_f32 v[148:149], v[170:171], v[152:153]
	v_sub_f32_e32 v165, v150, v151
	v_pk_mul_f32 v[150:151], v[172:173], v[152:153]
	v_add_f32_e32 v152, v148, v149
	v_pk_mul_f32 v[148:149], v[174:175], v[154:155]
	v_sub_f32_e32 v153, v150, v151
	v_pk_mul_f32 v[150:151], v[176:177], v[154:155]
	v_add_f32_e32 v154, v148, v149
	v_pk_mul_f32 v[148:149], v[178:179], v[156:157]
	v_sub_f32_e32 v155, v150, v151
	v_pk_mul_f32 v[150:151], v[180:181], v[156:157]
	v_add_f32_e32 v156, v148, v149
	v_pk_mul_f32 v[148:149], v[182:183], v[158:159]
	v_sub_f32_e32 v157, v150, v151
	v_pk_mul_f32 v[150:151], v[184:185], v[158:159]
	v_add_f32_e32 v158, v148, v149
	v_pk_mul_f32 v[148:149], v[186:187], v[160:161]
	v_sub_f32_e32 v150, v150, v151
	v_add_f32_e32 v151, v148, v149
	v_mov_b32_e32 v148, v58
	v_mov_b32_e32 v149, v122
	v_pk_mul_f32 v[148:149], v[148:149], v[160:161]
	v_lshlrev_b32_e32 v166, 1, v188
	v_sub_f32_e32 v159, v148, v149
	v_mov_b32_e32 v148, v123
	v_mov_b32_e32 v149, v59
	v_pk_mul_f32 v[148:149], v[148:149], v[146:147]
	v_mov_b32_e32 v167, v29
	v_add_f32_e32 v160, v148, v149
	v_mov_b32_e32 v148, v59
	v_mov_b32_e32 v149, v123
	v_pk_mul_f32 v[146:147], v[148:149], v[146:147]
	v_mov_b32_e32 v168, v29
	v_sub_f32_e32 v161, v146, v147
	v_cvt_pk_bf16_f32 v226, v162, v164
	v_cvt_pk_bf16_f32 v227, v152, v154
	v_cvt_pk_bf16_f32 v228, v156, v158
	v_cvt_pk_bf16_f32 v229, v151, v160
	v_mov_b32_e32 v234, v166
	v_mov_b32_e32 v162, v138
	v_mov_b32_e32 v164, v28
	v_cvt_pk_bf16_f32 v230, v163, v165
	v_cvt_pk_bf16_f32 v231, v153, v155
	v_cvt_pk_bf16_f32 v232, v157, v150
	v_cvt_pk_bf16_f32 v233, v159, v161
	v_mov_b32_e32 v163, v28
	v_mov_b32_e32 v165, v92
	v_mul_lo_u32 v146, v162, v140
	v_ashrrev_i32_e32 v147, 31, v146
	v_lshl_add_u64 v[148:149], v[146:147], 3, s[26:27]
	v_add_u32_e32 v146, v146, v162
	v_ashrrev_i32_e32 v147, 31, v146
	v_lshl_add_u64 v[150:151], v[146:147], 3, s[26:27]
	v_add_u32_e32 v146, v146, v162
	v_ashrrev_i32_e32 v147, 31, v146
	global_load_dwordx2 v[148:149], v[148:149], off
	v_lshl_add_u64 v[152:153], v[146:147], 3, s[26:27]
	v_add_u32_e32 v146, v146, v162
	global_load_dwordx2 v[150:151], v[150:151], off
	v_ashrrev_i32_e32 v147, 31, v146
	global_load_dwordx2 v[152:153], v[152:153], off
	v_lshl_add_u64 v[154:155], v[146:147], 3, s[26:27]
	v_add_u32_e32 v146, v146, v162
	global_load_dwordx2 v[154:155], v[154:155], off
	v_ashrrev_i32_e32 v147, 31, v146
	v_lshl_add_u64 v[156:157], v[146:147], 3, s[26:27]
	global_load_dwordx2 v[156:157], v[156:157], off
	v_add_u32_e32 v146, v146, v162
	v_ashrrev_i32_e32 v147, 31, v146
	v_lshl_add_u64 v[158:159], v[146:147], 3, s[26:27]
	global_load_dwordx2 v[158:159], v[158:159], off
	v_add_u32_e32 v146, v146, v162
	v_ashrrev_i32_e32 v147, 31, v146
	v_lshl_add_u64 v[160:161], v[146:147], 3, s[26:27]
	global_load_dwordx2 v[160:161], v[160:161], off
	v_add_u32_e32 v146, v146, v162
	v_ashrrev_i32_e32 v147, 31, v146
	v_lshl_add_u64 v[146:147], v[146:147], 3, s[26:27]
	global_load_dwordx2 v[146:147], v[146:147], off
	buffer_store_dwordx4 v[226:229], v234, s[8:11], 0 offen sc1
	buffer_store_dwordx4 v[230:233], v234, s[8:11], 0 offen offset:128 sc1
	v_mov_b32_e32 v162, v92
	v_mov_b32_e32 v166, v93
	v_mov_b32_e32 v169, v93
	v_mov_b32_e32 v170, v94
	v_mov_b32_e32 v171, v30
	v_mov_b32_e32 v172, v30
	v_mov_b32_e32 v173, v94
	v_mov_b32_e32 v174, v95
	v_mov_b32_e32 v175, v31
	v_mov_b32_e32 v176, v31
	v_mov_b32_e32 v177, v95
	s_waitcnt vmcnt(9)
	v_pk_mul_f32 v[162:163], v[162:163], v[148:149]
	v_pk_mul_f32 v[148:149], v[164:165], v[148:149]
	v_add_f32_e32 v162, v162, v163
	v_sub_f32_e32 v163, v148, v149
	s_waitcnt vmcnt(8)
	v_pk_mul_f32 v[148:149], v[166:167], v[150:151]
	v_pk_mul_f32 v[150:151], v[168:169], v[150:151]
	v_add_f32_e32 v164, v148, v149
	s_waitcnt vmcnt(7)
	v_pk_mul_f32 v[148:149], v[170:171], v[152:153]
	v_sub_f32_e32 v165, v150, v151
	v_pk_mul_f32 v[150:151], v[172:173], v[152:153]
	v_add_f32_e32 v152, v148, v149
	s_waitcnt vmcnt(6)
	v_pk_mul_f32 v[148:149], v[174:175], v[154:155]
	v_sub_f32_e32 v153, v150, v151
	v_pk_mul_f32 v[150:151], v[176:177], v[154:155]
	v_add_f32_e32 v154, v148, v149
	v_mov_b32_e32 v148, v88
	v_mov_b32_e32 v149, v24
	s_waitcnt vmcnt(5)
	v_pk_mul_f32 v[148:149], v[148:149], v[156:157]
	v_sub_f32_e32 v150, v150, v151
	v_add_f32_e32 v151, v148, v149
	v_mov_b32_e32 v148, v24
	v_mov_b32_e32 v149, v88
	v_pk_mul_f32 v[148:149], v[148:149], v[156:157]
	v_mov_b32_e32 v166, v117
	v_sub_f32_e32 v155, v148, v149
	v_mov_b32_e32 v148, v89
	v_mov_b32_e32 v149, v25
	s_waitcnt vmcnt(4)
	v_pk_mul_f32 v[148:149], v[148:149], v[158:159]
	v_mov_b32_e32 v167, v53
	v_add_f32_e32 v156, v148, v149
	v_mov_b32_e32 v148, v25
	v_mov_b32_e32 v149, v89
	v_pk_mul_f32 v[148:149], v[148:149], v[158:159]
	s_nop 0
	v_sub_f32_e32 v157, v148, v149
	v_mov_b32_e32 v148, v90
	v_mov_b32_e32 v149, v26
	s_waitcnt vmcnt(3)
	v_pk_mul_f32 v[148:149], v[148:149], v[160:161]
	s_nop 0
	v_add_f32_e32 v158, v148, v149
	v_mov_b32_e32 v148, v26
	v_mov_b32_e32 v149, v90
	v_pk_mul_f32 v[148:149], v[148:149], v[160:161]
	s_nop 0
	v_sub_f32_e32 v159, v148, v149
	v_mov_b32_e32 v148, v91
	v_mov_b32_e32 v149, v27
	s_waitcnt vmcnt(2)
; __device__ __forceinline__ unsigned cvt_pk_bf16(float lo, float hi) { unsigned r; asm volatile("v_cvt_pk_bf16_f32 %0, %1, %2" : "=v"(r) : "v"(lo), "v"(hi)); return r; }
;     __device__ __forceinline__ void operator()(const f32x4 (&acc)[2][2][4][2], const Unit& u, int wr, int wc, int fr, int fq) const {
;     ...
;         for (int m = 0; m < 4; ++m) { const int k1 = 16 * m + fr;
; #pragma unroll
;             for (int bj = 0; bj < 2; ++bj) { const int col = 4 * u.pn + 2 * bj + (wc >> 1), b = col >> 8, ch = col & 255;
;                 const int n2 = 32 * (wc & 1) + 8 * fq;
;                 const unsigned rowo = (unsigned)((((size_t)(b * 64 + k1) * 256 + ch) * 128 + n2) * 2);
;                 int kk = k1; asm volatile("" : "+v"(kk));
;                 f32x4 pr[2], pi[2];
; #pragma unroll
;                 for (int n = 0; n < 2; ++n) { const f32x4 yr = acc[0][bj][m][n], yi = acc[1][bj][m][n];
; #pragma unroll
;                     for (int i = 0; i < 4; ++i) { const f32x2 cs = TW[(n2 + 4 * n + i) * kk]; pr[n][i] = yr[i] * cs.x + yi[i] * cs.y; pi[n][i] = yi[i] * cs.x - yr[i] * cs.y; } }
;                 u32x4 w; w.x = cvt_pk_bf16(pr[0][0], pr[0][1]); w.y = cvt_pk_bf16(pr[0][2], pr[0][3]); w.z = cvt_pk_bf16(pr[1][0], pr[1][1]); w.w = cvt_pk_bf16(pr[1][2], pr[1][3]);
;                 __builtin_amdgcn_raw_buffer_store_b128(w, rsrc, rowo, 0, 16);
;                 w.x = cvt_pk_bf16(pi[0][0], pi[0][1]); w.y = cvt_pk_bf16(pi[0][2], pi[0][3]); w.z = cvt_pk_bf16(pi[1][0], pi[1][1]); w.w = cvt_pk_bf16(pi[1][2], pi[1][3]);
;                 __builtin_amdgcn_raw_buffer_store_b128(w, rsrc, rowo + 128, 0, 16);
	v_pk_mul_f32 v[148:149], v[148:149], v[146:147]
	s_nop 0
	v_add_f32_e32 v160, v148, v149
	v_mov_b32_e32 v148, v27
	v_mov_b32_e32 v149, v91
	v_pk_mul_f32 v[146:147], v[148:149], v[146:147]
	s_nop 0
	v_sub_f32_e32 v161, v146, v147
	v_cvt_pk_bf16_f32 v226, v162, v164
	v_cvt_pk_bf16_f32 v227, v152, v154
	v_cvt_pk_bf16_f32 v228, v151, v156
	v_cvt_pk_bf16_f32 v229, v158, v160
	v_mov_b32_e32 v234, v145
	v_mov_b32_e32 v162, v116
	v_mov_b32_e32 v164, v52
	v_cvt_pk_bf16_f32 v230, v163, v165
	v_cvt_pk_bf16_f32 v231, v153, v150
	v_cvt_pk_bf16_f32 v232, v155, v157
	v_cvt_pk_bf16_f32 v233, v159, v161
	v_mov_b32_e32 v145, v141
	v_mov_b32_e32 v163, v52
	v_mul_lo_u32 v146, v145, v140
	v_ashrrev_i32_e32 v147, 31, v146
	v_lshl_add_u64 v[148:149], v[146:147], 3, s[26:27]
	v_add_u32_e32 v146, v146, v145
	v_ashrrev_i32_e32 v147, 31, v146
	global_load_dwordx2 v[148:149], v[148:149], off
	v_lshl_add_u64 v[150:151], v[146:147], 3, s[26:27]
	global_load_dwordx2 v[150:151], v[150:151], off
	v_add_u32_e32 v146, v146, v145
	v_ashrrev_i32_e32 v147, 31, v146
	v_lshl_add_u64 v[152:153], v[146:147], 3, s[26:27]
	global_load_dwordx2 v[152:153], v[152:153], off
	v_add_u32_e32 v146, v146, v145
	v_ashrrev_i32_e32 v147, 31, v146
	v_lshl_add_u64 v[154:155], v[146:147], 3, s[26:27]
	global_load_dwordx2 v[154:155], v[154:155], off
	v_add_u32_e32 v146, v146, v145
	v_ashrrev_i32_e32 v147, 31, v146
	v_lshl_add_u64 v[156:157], v[146:147], 3, s[26:27]
	global_load_dwordx2 v[156:157], v[156:157], off
	v_add_u32_e32 v146, v146, v145
	v_ashrrev_i32_e32 v147, 31, v146
	v_lshl_add_u64 v[158:159], v[146:147], 3, s[26:27]
	global_load_dwordx2 v[158:159], v[158:159], off
	v_add_u32_e32 v146, v146, v145
	v_ashrrev_i32_e32 v147, 31, v146
	v_lshl_add_u64 v[160:161], v[146:147], 3, s[26:27]
	global_load_dwordx2 v[160:161], v[160:161], off
	v_add_u32_e32 v146, v146, v145
	v_ashrrev_i32_e32 v147, 31, v146
	v_lshl_add_u64 v[146:147], v[146:147], 3, s[26:27]
	global_load_dwordx2 v[146:147], v[146:147], off
	buffer_store_dwordx4 v[226:229], v234, s[8:11], 0 offen sc1
	buffer_store_dwordx4 v[230:233], v234, s[8:11], 0 offen offset:128 sc1
	v_mov_b32_e32 v165, v116
	v_or_b32_e32 v145, s2, v141
	v_lshl_or_b32 v145, v145, 15, v140
	v_or_b32_e32 v168, s35, v145
	v_or_b32_e32 v145, s3, v145
	v_lshlrev_b32_e32 v145, 1, v145
	s_waitcnt vmcnt(9)
	v_pk_mul_f32 v[162:163], v[162:163], v[148:149]
	v_pk_mul_f32 v[148:149], v[164:165], v[148:149]
	v_add_f32_e32 v162, v162, v163
	v_sub_f32_e32 v163, v148, v149
	s_waitcnt vmcnt(8)
	v_pk_mul_f32 v[148:149], v[166:167], v[150:151]
	v_lshlrev_b32_e32 v166, 1, v168
	v_add_f32_e32 v164, v148, v149
	v_mov_b32_e32 v148, v53
	v_mov_b32_e32 v149, v117
	v_pk_mul_f32 v[148:149], v[148:149], v[150:151]
	s_nop 0
	v_sub_f32_e32 v150, v148, v149
	v_mov_b32_e32 v148, v118
	v_mov_b32_e32 v149, v54
	s_waitcnt vmcnt(7)
	v_pk_mul_f32 v[148:149], v[148:149], v[152:153]
	s_nop 0
	v_add_f32_e32 v151, v148, v149
	v_mov_b32_e32 v148, v54
	v_mov_b32_e32 v149, v118
	v_pk_mul_f32 v[148:149], v[148:149], v[152:153]
	s_nop 0
	v_sub_f32_e32 v152, v148, v149
	v_mov_b32_e32 v148, v119
	v_mov_b32_e32 v149, v55
	s_waitcnt vmcnt(6)
	v_pk_mul_f32 v[148:149], v[148:149], v[154:155]
	s_nop 0
	v_add_f32_e32 v153, v148, v149
	v_mov_b32_e32 v148, v55
	v_mov_b32_e32 v149, v119
	v_pk_mul_f32 v[148:149], v[148:149], v[154:155]
	s_nop 0
	v_sub_f32_e32 v154, v148, v149
	v_mov_b32_e32 v148, v112
	v_mov_b32_e32 v149, v48
	s_waitcnt vmcnt(5)
	v_pk_mul_f32 v[148:149], v[148:149], v[156:157]
	s_nop 0
	v_add_f32_e32 v155, v148, v149
	v_mov_b32_e32 v148, v48
	v_mov_b32_e32 v149, v112
	v_pk_mul_f32 v[148:149], v[148:149], v[156:157]
	s_nop 0
	v_sub_f32_e32 v156, v148, v149
	v_mov_b32_e32 v148, v113
	v_mov_b32_e32 v149, v49
	s_waitcnt vmcnt(4)
	v_pk_mul_f32 v[148:149], v[148:149], v[158:159]
	s_nop 0
	v_add_f32_e32 v157, v148, v149
	v_mov_b32_e32 v148, v49
	v_mov_b32_e32 v149, v113
	v_pk_mul_f32 v[148:149], v[148:149], v[158:159]
	s_nop 0
	v_sub_f32_e32 v158, v148, v149
	v_mov_b32_e32 v148, v114
	v_mov_b32_e32 v149, v50
	s_waitcnt vmcnt(3)
	v_pk_mul_f32 v[148:149], v[148:149], v[160:161]
	s_nop 0
	v_add_f32_e32 v159, v148, v149
	v_mov_b32_e32 v148, v50
	v_mov_b32_e32 v149, v114
	v_pk_mul_f32 v[148:149], v[148:149], v[160:161]
	s_nop 0
	v_sub_f32_e32 v160, v148, v149
	v_mov_b32_e32 v148, v115
	v_mov_b32_e32 v149, v51
	s_waitcnt vmcnt(2)
	v_pk_mul_f32 v[148:149], v[148:149], v[146:147]
	s_nop 0
	v_add_f32_e32 v161, v148, v149
	v_mov_b32_e32 v148, v51
	v_mov_b32_e32 v149, v115
	v_pk_mul_f32 v[146:147], v[148:149], v[146:147]
	s_nop 0
	v_sub_f32_e32 v165, v146, v147
	v_cvt_pk_bf16_f32 v226, v162, v164
	v_cvt_pk_bf16_f32 v227, v151, v153
	v_cvt_pk_bf16_f32 v228, v155, v157
	v_cvt_pk_bf16_f32 v229, v159, v161
	v_mov_b32_e32 v234, v166
	v_mov_b32_e32 v162, v141
	s_nop 0
	v_cvt_pk_bf16_f32 v230, v163, v150
	v_cvt_pk_bf16_f32 v231, v152, v154
	v_cvt_pk_bf16_f32 v232, v156, v158
	v_cvt_pk_bf16_f32 v233, v160, v165
	v_mov_b32_e32 v163, v20
	s_nop 0
	v_mul_lo_u32 v146, v162, v140
	v_ashrrev_i32_e32 v147, 31, v146
	v_lshl_add_u64 v[148:149], v[146:147], 3, s[26:27]
	global_load_dwordx2 v[148:149], v[148:149], off
	v_add_u32_e32 v146, v146, v162
	v_ashrrev_i32_e32 v147, 31, v146
	v_lshl_add_u64 v[150:151], v[146:147], 3, s[26:27]
	global_load_dwordx2 v[150:151], v[150:151], off
	v_add_u32_e32 v146, v146, v162
	v_ashrrev_i32_e32 v147, 31, v146
	v_lshl_add_u64 v[152:153], v[146:147], 3, s[26:27]
	global_load_dwordx2 v[152:153], v[152:153], off
	v_add_u32_e32 v146, v146, v162
	v_ashrrev_i32_e32 v147, 31, v146
	v_lshl_add_u64 v[154:155], v[146:147], 3, s[26:27]
	global_load_dwordx2 v[154:155], v[154:155], off
	v_add_u32_e32 v146, v146, v162
	v_ashrrev_i32_e32 v147, 31, v146
	v_lshl_add_u64 v[156:157], v[146:147], 3, s[26:27]
	global_load_dwordx2 v[156:157], v[156:157], off
	v_add_u32_e32 v146, v146, v162
	v_ashrrev_i32_e32 v147, 31, v146
	v_lshl_add_u64 v[158:159], v[146:147], 3, s[26:27]
	global_load_dwordx2 v[158:159], v[158:159], off
	v_add_u32_e32 v146, v146, v162
	v_ashrrev_i32_e32 v147, 31, v146
	v_lshl_add_u64 v[160:161], v[146:147], 3, s[26:27]
	global_load_dwordx2 v[160:161], v[160:161], off
	v_add_u32_e32 v146, v146, v162
	v_ashrrev_i32_e32 v147, 31, v146
	v_lshl_add_u64 v[146:147], v[146:147], 3, s[26:27]
	global_load_dwordx2 v[146:147], v[146:147], off
	buffer_store_dwordx4 v[226:229], v234, s[8:11], 0 offen sc1
	buffer_store_dwordx4 v[230:233], v234, s[8:11], 0 offen offset:128 sc1
	v_mov_b32_e32 v162, v84
	s_waitcnt vmcnt(9)
; __device__ __forceinline__ unsigned cvt_pk_bf16(float lo, float hi) { unsigned r; asm volatile("v_cvt_pk_bf16_f32 %0, %1, %2" : "=v"(r) : "v"(lo), "v"(hi)); return r; }
;     __device__ __forceinline__ void operator()(const f32x4 (&acc)[2][2][4][2], const Unit& u, int wr, int wc, int fr, int fq) const {
;     ...
;         for (int m = 0; m < 4; ++m) { const int k1 = 16 * m + fr;
; #pragma unroll
;             for (int bj = 0; bj < 2; ++bj) { const int col = 4 * u.pn + 2 * bj + (wc >> 1), b = col >> 8, ch = col & 255;
;                 const int n2 = 32 * (wc & 1) + 8 * fq;
;                 const unsigned rowo = (unsigned)((((size_t)(b * 64 + k1) * 256 + ch) * 128 + n2) * 2);
;                 int kk = k1; asm volatile("" : "+v"(kk));
;                 f32x4 pr[2], pi[2];
; #pragma unroll
;                 for (int n = 0; n < 2; ++n) { const f32x4 yr = acc[0][bj][m][n], yi = acc[1][bj][m][n];
; #pragma unroll
;                     for (int i = 0; i < 4; ++i) { const f32x2 cs = TW[(n2 + 4 * n + i) * kk]; pr[n][i] = yr[i] * cs.x + yi[i] * cs.y; pi[n][i] = yi[i] * cs.x - yr[i] * cs.y; } }
;                 u32x4 w; w.x = cvt_pk_bf16(pr[0][0], pr[0][1]); w.y = cvt_pk_bf16(pr[0][2], pr[0][3]); w.z = cvt_pk_bf16(pr[1][0], pr[1][1]); w.w = cvt_pk_bf16(pr[1][2], pr[1][3]);
;                 __builtin_amdgcn_raw_buffer_store_b128(w, rsrc, rowo, 0, 16);
;                 w.x = cvt_pk_bf16(pi[0][0], pi[0][1]); w.y = cvt_pk_bf16(pi[0][2], pi[0][3]); w.z = cvt_pk_bf16(pi[1][0], pi[1][1]); w.w = cvt_pk_bf16(pi[1][2], pi[1][3]);
;                 __builtin_amdgcn_raw_buffer_store_b128(w, rsrc, rowo + 128, 0, 16);
	v_pk_mul_f32 v[162:163], v[162:163], v[148:149]
	s_nop 0
	v_add_f32_e32 v164, v162, v163
	v_mov_b32_e32 v162, v20
	v_mov_b32_e32 v163, v84
	v_pk_mul_f32 v[148:149], v[162:163], v[148:149]
	s_nop 0
	v_sub_f32_e32 v162, v148, v149
	v_mov_b32_e32 v148, v85
	v_mov_b32_e32 v149, v21
	s_waitcnt vmcnt(8)
	v_pk_mul_f32 v[148:149], v[148:149], v[150:151]
	s_nop 0
	v_add_f32_e32 v163, v148, v149
	v_mov_b32_e32 v148, v21
	v_mov_b32_e32 v149, v85
	v_pk_mul_f32 v[148:149], v[148:149], v[150:151]
	s_nop 0
	v_sub_f32_e32 v150, v148, v149
	v_mov_b32_e32 v148, v86
	v_mov_b32_e32 v149, v22
	s_waitcnt vmcnt(7)
	v_pk_mul_f32 v[148:149], v[148:149], v[152:153]
	s_nop 0
	v_add_f32_e32 v151, v148, v149
	v_mov_b32_e32 v148, v22
	v_mov_b32_e32 v149, v86
	v_pk_mul_f32 v[148:149], v[148:149], v[152:153]
	s_nop 0
	v_sub_f32_e32 v152, v148, v149
	v_mov_b32_e32 v148, v87
	v_mov_b32_e32 v149, v23
	s_waitcnt vmcnt(6)
	v_pk_mul_f32 v[148:149], v[148:149], v[154:155]
	s_nop 0
	v_add_f32_e32 v153, v148, v149
	v_mov_b32_e32 v148, v23
	v_mov_b32_e32 v149, v87
	v_pk_mul_f32 v[148:149], v[148:149], v[154:155]
	s_nop 0
	v_sub_f32_e32 v154, v148, v149
	v_mov_b32_e32 v148, v80
	v_mov_b32_e32 v149, v16
	s_waitcnt vmcnt(5)
	v_pk_mul_f32 v[148:149], v[148:149], v[156:157]
	s_nop 0
	v_add_f32_e32 v155, v148, v149
	v_mov_b32_e32 v148, v16
	v_mov_b32_e32 v149, v80
	v_pk_mul_f32 v[148:149], v[148:149], v[156:157]
	s_nop 0
	v_sub_f32_e32 v156, v148, v149
	v_mov_b32_e32 v148, v81
	v_mov_b32_e32 v149, v17
	s_waitcnt vmcnt(4)
	v_pk_mul_f32 v[148:149], v[148:149], v[158:159]
	s_nop 0
	v_add_f32_e32 v157, v148, v149
	v_mov_b32_e32 v148, v17
	v_mov_b32_e32 v149, v81
	v_pk_mul_f32 v[148:149], v[148:149], v[158:159]
	s_nop 0
	v_sub_f32_e32 v158, v148, v149
	v_mov_b32_e32 v148, v82
	v_mov_b32_e32 v149, v18
	s_waitcnt vmcnt(3)
	v_pk_mul_f32 v[148:149], v[148:149], v[160:161]
	s_nop 0
	v_add_f32_e32 v159, v148, v149
	v_mov_b32_e32 v148, v18
	v_mov_b32_e32 v149, v82
	v_pk_mul_f32 v[148:149], v[148:149], v[160:161]
	s_nop 0
	v_sub_f32_e32 v160, v148, v149
	v_mov_b32_e32 v148, v83
	v_mov_b32_e32 v149, v19
	s_waitcnt vmcnt(2)
	v_pk_mul_f32 v[148:149], v[148:149], v[146:147]
	s_nop 0
	v_add_f32_e32 v161, v148, v149
	v_mov_b32_e32 v148, v19
	v_mov_b32_e32 v149, v83
	v_pk_mul_f32 v[146:147], v[148:149], v[146:147]
	s_nop 0
	v_sub_f32_e32 v165, v146, v147
	v_cvt_pk_bf16_f32 v226, v164, v163
	v_cvt_pk_bf16_f32 v227, v151, v153
	v_cvt_pk_bf16_f32 v228, v155, v157
	v_cvt_pk_bf16_f32 v229, v159, v161
	v_mov_b32_e32 v234, v145
	v_mov_b32_e32 v163, v44
	s_nop 0
	v_cvt_pk_bf16_f32 v230, v162, v150
	v_cvt_pk_bf16_f32 v231, v152, v154
	v_cvt_pk_bf16_f32 v232, v156, v158
	v_cvt_pk_bf16_f32 v233, v160, v165
	v_mov_b32_e32 v145, v142
	v_mov_b32_e32 v162, v108
	v_mul_lo_u32 v146, v145, v140
	v_ashrrev_i32_e32 v147, 31, v146
	v_lshl_add_u64 v[148:149], v[146:147], 3, s[26:27]
	global_load_dwordx2 v[148:149], v[148:149], off
	v_add_u32_e32 v146, v146, v145
	v_ashrrev_i32_e32 v147, 31, v146
	v_lshl_add_u64 v[150:151], v[146:147], 3, s[26:27]
	global_load_dwordx2 v[150:151], v[150:151], off
	v_add_u32_e32 v146, v146, v145
	v_ashrrev_i32_e32 v147, 31, v146
	v_lshl_add_u64 v[152:153], v[146:147], 3, s[26:27]
	global_load_dwordx2 v[152:153], v[152:153], off
	v_add_u32_e32 v146, v146, v145
	v_ashrrev_i32_e32 v147, 31, v146
	v_lshl_add_u64 v[154:155], v[146:147], 3, s[26:27]
	global_load_dwordx2 v[154:155], v[154:155], off
	v_add_u32_e32 v146, v146, v145
	v_ashrrev_i32_e32 v147, 31, v146
	v_lshl_add_u64 v[156:157], v[146:147], 3, s[26:27]
	global_load_dwordx2 v[156:157], v[156:157], off
	v_add_u32_e32 v146, v146, v145
	v_ashrrev_i32_e32 v147, 31, v146
	v_lshl_add_u64 v[158:159], v[146:147], 3, s[26:27]
	global_load_dwordx2 v[158:159], v[158:159], off
	v_add_u32_e32 v146, v146, v145
	v_ashrrev_i32_e32 v147, 31, v146
	v_lshl_add_u64 v[160:161], v[146:147], 3, s[26:27]
	global_load_dwordx2 v[160:161], v[160:161], off
	v_add_u32_e32 v146, v146, v145
	v_ashrrev_i32_e32 v147, 31, v146
	v_lshl_add_u64 v[146:147], v[146:147], 3, s[26:27]
	global_load_dwordx2 v[146:147], v[146:147], off
	buffer_store_dwordx4 v[226:229], v234, s[8:11], 0 offen sc1
	buffer_store_dwordx4 v[230:233], v234, s[8:11], 0 offen offset:128 sc1
	v_or_b32_e32 v145, s2, v142
	v_lshl_or_b32 v145, v145, 15, v140
	v_or_b32_e32 v164, s35, v145
	v_lshlrev_b32_e32 v164, 1, v164
	v_or_b32_e32 v145, s3, v145
	v_lshlrev_b32_e32 v145, 1, v145
	s_waitcnt vmcnt(9)
	v_pk_mul_f32 v[162:163], v[162:163], v[148:149]
	s_nop 0
	v_add_f32_e32 v165, v162, v163
	v_mov_b32_e32 v162, v44
	v_mov_b32_e32 v163, v108
	v_pk_mul_f32 v[148:149], v[162:163], v[148:149]
	s_nop 0
	v_sub_f32_e32 v162, v148, v149
	v_mov_b32_e32 v148, v109
	v_mov_b32_e32 v149, v45
	s_waitcnt vmcnt(8)
	v_pk_mul_f32 v[148:149], v[148:149], v[150:151]
	s_nop 0
	v_add_f32_e32 v163, v148, v149
	v_mov_b32_e32 v148, v45
	v_mov_b32_e32 v149, v109
	v_pk_mul_f32 v[148:149], v[148:149], v[150:151]
	s_nop 0
	v_sub_f32_e32 v150, v148, v149
	v_mov_b32_e32 v148, v110
	v_mov_b32_e32 v149, v46
	s_waitcnt vmcnt(7)
	v_pk_mul_f32 v[148:149], v[148:149], v[152:153]
	s_nop 0
	v_add_f32_e32 v151, v148, v149
	v_mov_b32_e32 v148, v46
	v_mov_b32_e32 v149, v110
	v_pk_mul_f32 v[148:149], v[148:149], v[152:153]
	s_nop 0
	v_sub_f32_e32 v152, v148, v149
	v_mov_b32_e32 v148, v111
	v_mov_b32_e32 v149, v47
	s_waitcnt vmcnt(6)
	v_pk_mul_f32 v[148:149], v[148:149], v[154:155]
	s_nop 0
	v_add_f32_e32 v153, v148, v149
	v_mov_b32_e32 v148, v47
	v_mov_b32_e32 v149, v111
	v_pk_mul_f32 v[148:149], v[148:149], v[154:155]
	s_nop 0
	v_sub_f32_e32 v154, v148, v149
	v_mov_b32_e32 v148, v104
	v_mov_b32_e32 v149, v40
	s_waitcnt vmcnt(5)
; __device__ __forceinline__ unsigned cvt_pk_bf16(float lo, float hi) { unsigned r; asm volatile("v_cvt_pk_bf16_f32 %0, %1, %2" : "=v"(r) : "v"(lo), "v"(hi)); return r; }
;     __device__ __forceinline__ void operator()(const f32x4 (&acc)[2][2][4][2], const Unit& u, int wr, int wc, int fr, int fq) const {
;     ...
;         for (int m = 0; m < 4; ++m) { const int k1 = 16 * m + fr;
; #pragma unroll
;             for (int bj = 0; bj < 2; ++bj) { const int col = 4 * u.pn + 2 * bj + (wc >> 1), b = col >> 8, ch = col & 255;
;                 const int n2 = 32 * (wc & 1) + 8 * fq;
;                 const unsigned rowo = (unsigned)((((size_t)(b * 64 + k1) * 256 + ch) * 128 + n2) * 2);
;                 int kk = k1; asm volatile("" : "+v"(kk));
;                 f32x4 pr[2], pi[2];
; #pragma unroll
;                 for (int n = 0; n < 2; ++n) { const f32x4 yr = acc[0][bj][m][n], yi = acc[1][bj][m][n];
; #pragma unroll
;                     for (int i = 0; i < 4; ++i) { const f32x2 cs = TW[(n2 + 4 * n + i) * kk]; pr[n][i] = yr[i] * cs.x + yi[i] * cs.y; pi[n][i] = yi[i] * cs.x - yr[i] * cs.y; } }
;                 u32x4 w; w.x = cvt_pk_bf16(pr[0][0], pr[0][1]); w.y = cvt_pk_bf16(pr[0][2], pr[0][3]); w.z = cvt_pk_bf16(pr[1][0], pr[1][1]); w.w = cvt_pk_bf16(pr[1][2], pr[1][3]);
;                 __builtin_amdgcn_raw_buffer_store_b128(w, rsrc, rowo, 0, 16);
;                 w.x = cvt_pk_bf16(pi[0][0], pi[0][1]); w.y = cvt_pk_bf16(pi[0][2], pi[0][3]); w.z = cvt_pk_bf16(pi[1][0], pi[1][1]); w.w = cvt_pk_bf16(pi[1][2], pi[1][3]);
;                 __builtin_amdgcn_raw_buffer_store_b128(w, rsrc, rowo + 128, 0, 16);
	v_pk_mul_f32 v[148:149], v[148:149], v[156:157]
	s_nop 0
	v_add_f32_e32 v155, v148, v149
	v_mov_b32_e32 v148, v40
	v_mov_b32_e32 v149, v104
	v_pk_mul_f32 v[148:149], v[148:149], v[156:157]
	s_nop 0
	v_sub_f32_e32 v156, v148, v149
	v_mov_b32_e32 v148, v105
	v_mov_b32_e32 v149, v41
	s_waitcnt vmcnt(4)
	v_pk_mul_f32 v[148:149], v[148:149], v[158:159]
	s_nop 0
	v_add_f32_e32 v157, v148, v149
	v_mov_b32_e32 v148, v41
	v_mov_b32_e32 v149, v105
	v_pk_mul_f32 v[148:149], v[148:149], v[158:159]
	s_nop 0
	v_sub_f32_e32 v158, v148, v149
	v_mov_b32_e32 v148, v106
	v_mov_b32_e32 v149, v42
	s_waitcnt vmcnt(3)
	v_pk_mul_f32 v[148:149], v[148:149], v[160:161]
	s_nop 0
	v_add_f32_e32 v159, v148, v149
	v_mov_b32_e32 v148, v42
	v_mov_b32_e32 v149, v106
	v_pk_mul_f32 v[148:149], v[148:149], v[160:161]
	s_nop 0
	v_sub_f32_e32 v160, v148, v149
	v_mov_b32_e32 v148, v107
	v_mov_b32_e32 v149, v43
	s_waitcnt vmcnt(2)
	v_pk_mul_f32 v[148:149], v[148:149], v[146:147]
	s_nop 0
	v_add_f32_e32 v161, v148, v149
	v_mov_b32_e32 v148, v43
	v_mov_b32_e32 v149, v107
	v_pk_mul_f32 v[146:147], v[148:149], v[146:147]
	s_nop 0
	v_sub_f32_e32 v166, v146, v147
	v_cvt_pk_bf16_f32 v226, v165, v163
	v_cvt_pk_bf16_f32 v227, v151, v153
	v_cvt_pk_bf16_f32 v228, v155, v157
	v_cvt_pk_bf16_f32 v229, v159, v161
	v_mov_b32_e32 v234, v164
	v_mov_b32_e32 v163, v12
	s_nop 0
	v_cvt_pk_bf16_f32 v230, v162, v150
	v_cvt_pk_bf16_f32 v231, v152, v154
	v_cvt_pk_bf16_f32 v232, v156, v158
	v_cvt_pk_bf16_f32 v233, v160, v166
	v_mov_b32_e32 v162, v142
	s_nop 0
	v_mul_lo_u32 v146, v162, v140
	v_ashrrev_i32_e32 v147, 31, v146
	v_lshl_add_u64 v[148:149], v[146:147], 3, s[26:27]
	global_load_dwordx2 v[148:149], v[148:149], off
	v_add_u32_e32 v146, v146, v162
	v_ashrrev_i32_e32 v147, 31, v146
	v_lshl_add_u64 v[150:151], v[146:147], 3, s[26:27]
	global_load_dwordx2 v[150:151], v[150:151], off
	v_add_u32_e32 v146, v146, v162
	v_ashrrev_i32_e32 v147, 31, v146
	v_lshl_add_u64 v[152:153], v[146:147], 3, s[26:27]
	global_load_dwordx2 v[152:153], v[152:153], off
	v_add_u32_e32 v146, v146, v162
	v_ashrrev_i32_e32 v147, 31, v146
	v_lshl_add_u64 v[154:155], v[146:147], 3, s[26:27]
	global_load_dwordx2 v[154:155], v[154:155], off
	v_add_u32_e32 v146, v146, v162
	v_ashrrev_i32_e32 v147, 31, v146
	v_lshl_add_u64 v[156:157], v[146:147], 3, s[26:27]
	global_load_dwordx2 v[156:157], v[156:157], off
	v_add_u32_e32 v146, v146, v162
	v_ashrrev_i32_e32 v147, 31, v146
	v_lshl_add_u64 v[158:159], v[146:147], 3, s[26:27]
	global_load_dwordx2 v[158:159], v[158:159], off
	v_add_u32_e32 v146, v146, v162
	v_ashrrev_i32_e32 v147, 31, v146
	v_lshl_add_u64 v[160:161], v[146:147], 3, s[26:27]
	global_load_dwordx2 v[160:161], v[160:161], off
	v_add_u32_e32 v146, v146, v162
	v_ashrrev_i32_e32 v147, 31, v146
	v_lshl_add_u64 v[146:147], v[146:147], 3, s[26:27]
	global_load_dwordx2 v[146:147], v[146:147], off
	buffer_store_dwordx4 v[226:229], v234, s[8:11], 0 offen sc1
	buffer_store_dwordx4 v[230:233], v234, s[8:11], 0 offen offset:128 sc1
	v_mov_b32_e32 v162, v76
	s_waitcnt vmcnt(9)
	v_pk_mul_f32 v[162:163], v[162:163], v[148:149]
	s_nop 0
	v_add_f32_e32 v164, v162, v163
	v_mov_b32_e32 v162, v12
	v_mov_b32_e32 v163, v76
	v_pk_mul_f32 v[148:149], v[162:163], v[148:149]
	s_nop 0
	v_sub_f32_e32 v162, v148, v149
	v_mov_b32_e32 v148, v77
	v_mov_b32_e32 v149, v13
	s_waitcnt vmcnt(8)
	v_pk_mul_f32 v[148:149], v[148:149], v[150:151]
	s_nop 0
	v_add_f32_e32 v163, v148, v149
	v_mov_b32_e32 v148, v13
	v_mov_b32_e32 v149, v77
	v_pk_mul_f32 v[148:149], v[148:149], v[150:151]
	s_nop 0
	v_sub_f32_e32 v150, v148, v149
	v_mov_b32_e32 v148, v78
	v_mov_b32_e32 v149, v14
	s_waitcnt vmcnt(7)
	v_pk_mul_f32 v[148:149], v[148:149], v[152:153]
	s_nop 0
	v_add_f32_e32 v151, v148, v149
	v_mov_b32_e32 v148, v14
	v_mov_b32_e32 v149, v78
	v_pk_mul_f32 v[148:149], v[148:149], v[152:153]
	s_nop 0
	v_sub_f32_e32 v152, v148, v149
	v_mov_b32_e32 v148, v79
	v_mov_b32_e32 v149, v15
	s_waitcnt vmcnt(6)
	v_pk_mul_f32 v[148:149], v[148:149], v[154:155]
	s_nop 0
	v_add_f32_e32 v153, v148, v149
	v_mov_b32_e32 v148, v15
	v_mov_b32_e32 v149, v79
	v_pk_mul_f32 v[148:149], v[148:149], v[154:155]
	s_nop 0
	v_sub_f32_e32 v154, v148, v149
	v_mov_b32_e32 v148, v72
	v_mov_b32_e32 v149, v8
	s_waitcnt vmcnt(5)
	v_pk_mul_f32 v[148:149], v[148:149], v[156:157]
	s_nop 0
	v_add_f32_e32 v155, v148, v149
	v_mov_b32_e32 v148, v8
	v_mov_b32_e32 v149, v72
	v_pk_mul_f32 v[148:149], v[148:149], v[156:157]
	s_nop 0
	v_sub_f32_e32 v156, v148, v149
	v_mov_b32_e32 v148, v73
	v_mov_b32_e32 v149, v9
	s_waitcnt vmcnt(4)
	v_pk_mul_f32 v[148:149], v[148:149], v[158:159]
	s_nop 0
	v_add_f32_e32 v157, v148, v149
	v_mov_b32_e32 v148, v9
	v_mov_b32_e32 v149, v73
	v_pk_mul_f32 v[148:149], v[148:149], v[158:159]
	s_nop 0
	v_sub_f32_e32 v158, v148, v149
	v_mov_b32_e32 v148, v74
	v_mov_b32_e32 v149, v10
	s_waitcnt vmcnt(3)
	v_pk_mul_f32 v[148:149], v[148:149], v[160:161]
	s_nop 0
	v_add_f32_e32 v159, v148, v149
	v_mov_b32_e32 v148, v10
	v_mov_b32_e32 v149, v74
	v_pk_mul_f32 v[148:149], v[148:149], v[160:161]
	s_nop 0
	v_sub_f32_e32 v160, v148, v149
	v_mov_b32_e32 v148, v75
	v_mov_b32_e32 v149, v11
	s_waitcnt vmcnt(2)
; __device__ __forceinline__ unsigned cvt_pk_bf16(float lo, float hi) { unsigned r; asm volatile("v_cvt_pk_bf16_f32 %0, %1, %2" : "=v"(r) : "v"(lo), "v"(hi)); return r; }
;     __device__ __forceinline__ void operator()(const f32x4 (&acc)[2][2][4][2], const Unit& u, int wr, int wc, int fr, int fq) const {
;     ...
;         for (int m = 0; m < 4; ++m) { const int k1 = 16 * m + fr;
; #pragma unroll
;             for (int bj = 0; bj < 2; ++bj) { const int col = 4 * u.pn + 2 * bj + (wc >> 1), b = col >> 8, ch = col & 255;
;                 const int n2 = 32 * (wc & 1) + 8 * fq;
;                 const unsigned rowo = (unsigned)((((size_t)(b * 64 + k1) * 256 + ch) * 128 + n2) * 2);
;                 int kk = k1; asm volatile("" : "+v"(kk));
;                 f32x4 pr[2], pi[2];
; #pragma unroll
;                 for (int n = 0; n < 2; ++n) { const f32x4 yr = acc[0][bj][m][n], yi = acc[1][bj][m][n];
; #pragma unroll
;                     for (int i = 0; i < 4; ++i) { const f32x2 cs = TW[(n2 + 4 * n + i) * kk]; pr[n][i] = yr[i] * cs.x + yi[i] * cs.y; pi[n][i] = yi[i] * cs.x - yr[i] * cs.y; } }
;                 u32x4 w; w.x = cvt_pk_bf16(pr[0][0], pr[0][1]); w.y = cvt_pk_bf16(pr[0][2], pr[0][3]); w.z = cvt_pk_bf16(pr[1][0], pr[1][1]); w.w = cvt_pk_bf16(pr[1][2], pr[1][3]);
;                 __builtin_amdgcn_raw_buffer_store_b128(w, rsrc, rowo, 0, 16);
;                 w.x = cvt_pk_bf16(pi[0][0], pi[0][1]); w.y = cvt_pk_bf16(pi[0][2], pi[0][3]); w.z = cvt_pk_bf16(pi[1][0], pi[1][1]); w.w = cvt_pk_bf16(pi[1][2], pi[1][3]);
;                 __builtin_amdgcn_raw_buffer_store_b128(w, rsrc, rowo + 128, 0, 16);
	v_pk_mul_f32 v[148:149], v[148:149], v[146:147]
	s_nop 0
	v_add_f32_e32 v161, v148, v149
	v_mov_b32_e32 v148, v11
	v_mov_b32_e32 v149, v75
	v_pk_mul_f32 v[146:147], v[148:149], v[146:147]
	s_nop 0
	v_sub_f32_e32 v165, v146, v147
	v_cvt_pk_bf16_f32 v226, v164, v163
	v_cvt_pk_bf16_f32 v227, v151, v153
	v_cvt_pk_bf16_f32 v228, v155, v157
	v_cvt_pk_bf16_f32 v229, v159, v161
	v_mov_b32_e32 v234, v145
	v_mov_b32_e32 v163, v36
	s_nop 0
	v_cvt_pk_bf16_f32 v230, v162, v150
	v_cvt_pk_bf16_f32 v231, v152, v154
	v_cvt_pk_bf16_f32 v232, v156, v158
	v_cvt_pk_bf16_f32 v233, v160, v165
	v_mov_b32_e32 v145, v143
	v_mov_b32_e32 v162, v100
	v_mul_lo_u32 v146, v145, v140
	v_ashrrev_i32_e32 v147, 31, v146
	v_lshl_add_u64 v[148:149], v[146:147], 3, s[26:27]
	global_load_dwordx2 v[148:149], v[148:149], off
	v_add_u32_e32 v146, v146, v145
	v_ashrrev_i32_e32 v147, 31, v146
	v_lshl_add_u64 v[150:151], v[146:147], 3, s[26:27]
	global_load_dwordx2 v[150:151], v[150:151], off
	v_add_u32_e32 v146, v146, v145
	v_ashrrev_i32_e32 v147, 31, v146
	v_lshl_add_u64 v[152:153], v[146:147], 3, s[26:27]
	global_load_dwordx2 v[152:153], v[152:153], off
	v_add_u32_e32 v146, v146, v145
	v_ashrrev_i32_e32 v147, 31, v146
	v_lshl_add_u64 v[154:155], v[146:147], 3, s[26:27]
	global_load_dwordx2 v[154:155], v[154:155], off
	v_add_u32_e32 v146, v146, v145
	v_ashrrev_i32_e32 v147, 31, v146
	v_lshl_add_u64 v[156:157], v[146:147], 3, s[26:27]
	global_load_dwordx2 v[156:157], v[156:157], off
	v_add_u32_e32 v146, v146, v145
	v_ashrrev_i32_e32 v147, 31, v146
	v_lshl_add_u64 v[158:159], v[146:147], 3, s[26:27]
	global_load_dwordx2 v[158:159], v[158:159], off
	v_add_u32_e32 v146, v146, v145
	v_ashrrev_i32_e32 v147, 31, v146
	v_lshl_add_u64 v[160:161], v[146:147], 3, s[26:27]
	global_load_dwordx2 v[160:161], v[160:161], off
	v_add_u32_e32 v146, v146, v145
	v_ashrrev_i32_e32 v147, 31, v146
	v_lshl_add_u64 v[146:147], v[146:147], 3, s[26:27]
	global_load_dwordx2 v[146:147], v[146:147], off
	buffer_store_dwordx4 v[226:229], v234, s[8:11], 0 offen sc1
	buffer_store_dwordx4 v[230:233], v234, s[8:11], 0 offen offset:128 sc1
	v_or_b32_e32 v145, s2, v143
	v_lshl_or_b32 v145, v145, 15, v140
	v_or_b32_e32 v164, s35, v145
	v_lshlrev_b32_e32 v164, 1, v164
	v_or_b32_e32 v145, s3, v145
	v_lshlrev_b32_e32 v145, 1, v145
	s_waitcnt vmcnt(9)
	v_pk_mul_f32 v[162:163], v[162:163], v[148:149]
	s_nop 0
	v_add_f32_e32 v165, v162, v163
	v_mov_b32_e32 v162, v36
	v_mov_b32_e32 v163, v100
	v_pk_mul_f32 v[148:149], v[162:163], v[148:149]
	s_nop 0
	v_sub_f32_e32 v162, v148, v149
	v_mov_b32_e32 v148, v101
	v_mov_b32_e32 v149, v37
	s_waitcnt vmcnt(8)
	v_pk_mul_f32 v[148:149], v[148:149], v[150:151]
	s_nop 0
	v_add_f32_e32 v163, v148, v149
	v_mov_b32_e32 v148, v37
	v_mov_b32_e32 v149, v101
	v_pk_mul_f32 v[148:149], v[148:149], v[150:151]
	s_nop 0
	v_sub_f32_e32 v150, v148, v149
	v_mov_b32_e32 v148, v102
	v_mov_b32_e32 v149, v38
	s_waitcnt vmcnt(7)
	v_pk_mul_f32 v[148:149], v[148:149], v[152:153]
	s_nop 0
	v_add_f32_e32 v151, v148, v149
	v_mov_b32_e32 v148, v38
	v_mov_b32_e32 v149, v102
	v_pk_mul_f32 v[148:149], v[148:149], v[152:153]
	s_nop 0
	v_sub_f32_e32 v152, v148, v149
	v_mov_b32_e32 v148, v103
	v_mov_b32_e32 v149, v39
	s_waitcnt vmcnt(6)
	v_pk_mul_f32 v[148:149], v[148:149], v[154:155]
	s_nop 0
	v_add_f32_e32 v153, v148, v149
	v_mov_b32_e32 v148, v39
	v_mov_b32_e32 v149, v103
	v_pk_mul_f32 v[148:149], v[148:149], v[154:155]
	s_nop 0
	v_sub_f32_e32 v154, v148, v149
	v_mov_b32_e32 v148, v96
	v_mov_b32_e32 v149, v32
	s_waitcnt vmcnt(5)
	v_pk_mul_f32 v[148:149], v[148:149], v[156:157]
	s_nop 0
	v_add_f32_e32 v155, v148, v149
	v_mov_b32_e32 v148, v32
	v_mov_b32_e32 v149, v96
	v_pk_mul_f32 v[148:149], v[148:149], v[156:157]
	s_nop 0
	v_sub_f32_e32 v156, v148, v149
	v_mov_b32_e32 v148, v97
	v_mov_b32_e32 v149, v33
	s_waitcnt vmcnt(4)
	v_pk_mul_f32 v[148:149], v[148:149], v[158:159]
	s_nop 0
	v_add_f32_e32 v157, v148, v149
	v_mov_b32_e32 v148, v33
	v_mov_b32_e32 v149, v97
	v_pk_mul_f32 v[148:149], v[148:149], v[158:159]
	s_nop 0
	v_sub_f32_e32 v158, v148, v149
	v_mov_b32_e32 v148, v98
	v_mov_b32_e32 v149, v34
	s_waitcnt vmcnt(3)
	v_pk_mul_f32 v[148:149], v[148:149], v[160:161]
	s_nop 0
	v_add_f32_e32 v159, v148, v149
	v_mov_b32_e32 v148, v34
	v_mov_b32_e32 v149, v98
	v_pk_mul_f32 v[148:149], v[148:149], v[160:161]
	s_nop 0
	v_sub_f32_e32 v160, v148, v149
	v_mov_b32_e32 v148, v99
	v_mov_b32_e32 v149, v35
	s_waitcnt vmcnt(2)
; __device__ __forceinline__ unsigned cvt_pk_bf16(float lo, float hi) { unsigned r; asm volatile("v_cvt_pk_bf16_f32 %0, %1, %2" : "=v"(r) : "v"(lo), "v"(hi)); return r; }
;     __device__ __forceinline__ void operator()(const f32x4 (&acc)[2][2][4][2], const Unit& u, int wr, int wc, int fr, int fq) const {
;     ...
;         for (int m = 0; m < 4; ++m) { const int k1 = 16 * m + fr;
; #pragma unroll
;             for (int bj = 0; bj < 2; ++bj) { const int col = 4 * u.pn + 2 * bj + (wc >> 1), b = col >> 8, ch = col & 255;
;                 const int n2 = 32 * (wc & 1) + 8 * fq;
;                 const unsigned rowo = (unsigned)((((size_t)(b * 64 + k1) * 256 + ch) * 128 + n2) * 2);
;                 int kk = k1; asm volatile("" : "+v"(kk));
;                 f32x4 pr[2], pi[2];
; #pragma unroll
;                 for (int n = 0; n < 2; ++n) { const f32x4 yr = acc[0][bj][m][n], yi = acc[1][bj][m][n];
; #pragma unroll
;                     for (int i = 0; i < 4; ++i) { const f32x2 cs = TW[(n2 + 4 * n + i) * kk]; pr[n][i] = yr[i] * cs.x + yi[i] * cs.y; pi[n][i] = yi[i] * cs.x - yr[i] * cs.y; } }
;                 u32x4 w; w.x = cvt_pk_bf16(pr[0][0], pr[0][1]); w.y = cvt_pk_bf16(pr[0][2], pr[0][3]); w.z = cvt_pk_bf16(pr[1][0], pr[1][1]); w.w = cvt_pk_bf16(pr[1][2], pr[1][3]);
;                 __builtin_amdgcn_raw_buffer_store_b128(w, rsrc, rowo, 0, 16);
;                 w.x = cvt_pk_bf16(pi[0][0], pi[0][1]); w.y = cvt_pk_bf16(pi[0][2], pi[0][3]); w.z = cvt_pk_bf16(pi[1][0], pi[1][1]); w.w = cvt_pk_bf16(pi[1][2], pi[1][3]);
;                 __builtin_amdgcn_raw_buffer_store_b128(w, rsrc, rowo + 128, 0, 16);
;                 asm volatile("" ::: "memory"); } }
	v_pk_mul_f32 v[148:149], v[148:149], v[146:147]
	s_nop 0
	v_add_f32_e32 v161, v148, v149
	v_mov_b32_e32 v148, v35
	v_mov_b32_e32 v149, v99
	v_pk_mul_f32 v[146:147], v[148:149], v[146:147]
	s_nop 0
	v_sub_f32_e32 v166, v146, v147
	v_cvt_pk_bf16_f32 v226, v165, v163
	v_cvt_pk_bf16_f32 v227, v151, v153
	v_cvt_pk_bf16_f32 v228, v155, v157
	v_cvt_pk_bf16_f32 v229, v159, v161
	v_mov_b32_e32 v234, v164
	v_mov_b32_e32 v163, v4
	s_nop 0
	v_cvt_pk_bf16_f32 v230, v162, v150
	v_cvt_pk_bf16_f32 v231, v152, v154
	v_cvt_pk_bf16_f32 v232, v156, v158
	v_cvt_pk_bf16_f32 v233, v160, v166
	v_mov_b32_e32 v162, v143
	s_nop 0
	v_mul_lo_u32 v146, v162, v140
	v_ashrrev_i32_e32 v147, 31, v146
	v_lshl_add_u64 v[148:149], v[146:147], 3, s[26:27]
	global_load_dwordx2 v[148:149], v[148:149], off
	v_add_u32_e32 v146, v146, v162
	v_ashrrev_i32_e32 v147, 31, v146
	v_lshl_add_u64 v[150:151], v[146:147], 3, s[26:27]
	global_load_dwordx2 v[150:151], v[150:151], off
	v_add_u32_e32 v146, v146, v162
	v_ashrrev_i32_e32 v147, 31, v146
	v_lshl_add_u64 v[152:153], v[146:147], 3, s[26:27]
	global_load_dwordx2 v[152:153], v[152:153], off
	v_add_u32_e32 v146, v146, v162
	v_ashrrev_i32_e32 v147, 31, v146
	v_lshl_add_u64 v[154:155], v[146:147], 3, s[26:27]
	global_load_dwordx2 v[154:155], v[154:155], off
	v_add_u32_e32 v146, v146, v162
	v_ashrrev_i32_e32 v147, 31, v146
	v_lshl_add_u64 v[156:157], v[146:147], 3, s[26:27]
	global_load_dwordx2 v[156:157], v[156:157], off
	v_add_u32_e32 v146, v146, v162
	v_ashrrev_i32_e32 v147, 31, v146
	v_lshl_add_u64 v[158:159], v[146:147], 3, s[26:27]
	global_load_dwordx2 v[158:159], v[158:159], off
	v_add_u32_e32 v146, v146, v162
	v_ashrrev_i32_e32 v147, 31, v146
	v_lshl_add_u64 v[160:161], v[146:147], 3, s[26:27]
	global_load_dwordx2 v[160:161], v[160:161], off
	v_add_u32_e32 v146, v146, v162
	v_ashrrev_i32_e32 v147, 31, v146
	v_lshl_add_u64 v[146:147], v[146:147], 3, s[26:27]
	global_load_dwordx2 v[146:147], v[146:147], off
	buffer_store_dwordx4 v[226:229], v234, s[8:11], 0 offen sc1
	buffer_store_dwordx4 v[230:233], v234, s[8:11], 0 offen offset:128 sc1
	v_mov_b32_e32 v162, v68
	s_waitcnt vmcnt(9)
	v_pk_mul_f32 v[162:163], v[162:163], v[148:149]
	s_nop 0
	v_add_f32_e32 v164, v162, v163
	v_mov_b32_e32 v162, v4
	v_mov_b32_e32 v163, v68
	v_pk_mul_f32 v[148:149], v[162:163], v[148:149]
	s_nop 0
	v_sub_f32_e32 v162, v148, v149
	v_mov_b32_e32 v148, v69
	v_mov_b32_e32 v149, v5
	s_waitcnt vmcnt(8)
	v_pk_mul_f32 v[148:149], v[148:149], v[150:151]
	s_nop 0
	v_add_f32_e32 v163, v148, v149
	v_mov_b32_e32 v148, v5
	v_mov_b32_e32 v149, v69
	v_pk_mul_f32 v[148:149], v[148:149], v[150:151]
	s_nop 0
	v_sub_f32_e32 v150, v148, v149
	v_mov_b32_e32 v148, v70
	v_mov_b32_e32 v149, v6
	s_waitcnt vmcnt(7)
	v_pk_mul_f32 v[148:149], v[148:149], v[152:153]
	s_nop 0
	v_add_f32_e32 v151, v148, v149
	v_mov_b32_e32 v148, v6
	v_mov_b32_e32 v149, v70
	v_pk_mul_f32 v[148:149], v[148:149], v[152:153]
	s_nop 0
	v_sub_f32_e32 v152, v148, v149
	v_mov_b32_e32 v148, v71
	v_mov_b32_e32 v149, v7
	s_waitcnt vmcnt(6)
	v_pk_mul_f32 v[148:149], v[148:149], v[154:155]
	s_nop 0
	v_add_f32_e32 v153, v148, v149
	v_mov_b32_e32 v148, v7
	v_mov_b32_e32 v149, v71
	v_pk_mul_f32 v[148:149], v[148:149], v[154:155]
	s_nop 0
	v_sub_f32_e32 v154, v148, v149
	v_mov_b32_e32 v148, v64
	v_mov_b32_e32 v149, v0
	s_waitcnt vmcnt(5)
	v_pk_mul_f32 v[148:149], v[148:149], v[156:157]
	s_nop 0
	v_add_f32_e32 v155, v148, v149
	v_mov_b32_e32 v148, v0
	v_mov_b32_e32 v149, v64
	v_pk_mul_f32 v[148:149], v[148:149], v[156:157]
	s_nop 0
	v_sub_f32_e32 v156, v148, v149
	v_mov_b32_e32 v148, v65
	v_mov_b32_e32 v149, v1
	s_waitcnt vmcnt(4)
	v_pk_mul_f32 v[148:149], v[148:149], v[158:159]
	s_nop 0
	v_add_f32_e32 v157, v148, v149
	v_mov_b32_e32 v148, v1
	v_mov_b32_e32 v149, v65
	v_pk_mul_f32 v[148:149], v[148:149], v[158:159]
	s_nop 0
	v_sub_f32_e32 v158, v148, v149
	v_mov_b32_e32 v148, v66
	v_mov_b32_e32 v149, v2
	s_waitcnt vmcnt(3)
	v_pk_mul_f32 v[148:149], v[148:149], v[160:161]
	s_nop 0
	v_add_f32_e32 v159, v148, v149
	v_mov_b32_e32 v148, v2
	v_mov_b32_e32 v149, v66
	v_pk_mul_f32 v[148:149], v[148:149], v[160:161]
	s_nop 0
	v_sub_f32_e32 v160, v148, v149
	v_mov_b32_e32 v148, v67
	v_mov_b32_e32 v149, v3
	s_waitcnt vmcnt(2)
	v_pk_mul_f32 v[148:149], v[148:149], v[146:147]
	s_nop 0
	v_add_f32_e32 v161, v148, v149
	v_mov_b32_e32 v148, v3
	v_mov_b32_e32 v149, v67
	v_pk_mul_f32 v[146:147], v[148:149], v[146:147]
	s_nop 0
	v_sub_f32_e32 v165, v146, v147
	v_cvt_pk_bf16_f32 v146, v164, v163
	v_cvt_pk_bf16_f32 v147, v151, v153
	v_cvt_pk_bf16_f32 v148, v155, v157
	v_cvt_pk_bf16_f32 v149, v159, v161
	buffer_store_dwordx4 v[146:149], v145, s[8:11], 0 offen sc1
	s_nop 1
	v_cvt_pk_bf16_f32 v146, v162, v150
	v_cvt_pk_bf16_f32 v147, v152, v154
	v_cvt_pk_bf16_f32 v148, v156, v158
	v_cvt_pk_bf16_f32 v149, v160, v165
	buffer_store_dwordx4 v[146:149], v145, s[8:11], 0 offen offset:128 sc1
	s_andn2_b64 vcc, exec, s[40:41]
	s_cbranch_vccnz .LBB0_820
	s_branch .LBB0_829
